# phase-0 memory-token f32->bf16 conversion: the four row loads issued together instead of load/wait one at a time
# speedup vs baseline: 1.0019x; 1.0010x over previous
; __device__ __forceinline__ unsigned cvt_pk_bf16(float lo, float hi) { unsigned r; asm("v_cvt_pk_bf16_f32 %0, %1, %2" : "=v"(r) : "v"(lo), "v"(hi)); return r; }
; __global__ void __launch_bounds__(512, 2) mega_fwd(Args args) {
;     ...
;             for (int m = gw; m < MEMROWS; m += NGW) {
;                 const float* src = (m < 4096) ? args.in[2] + (size_t)m * D : args.in[3] + (size_t)(m - 4096) * D;
; #pragma unroll
;                 for (int j = 0; j < 4; ++j) { const f32x4 v = *((const f32x4*)src + lane + 64 * j); u32x2 w; w.x = cvt_pk_bf16(v[0], v[1]); w.y = cvt_pk_bf16(v[2], v[3]); *((u32x2*)(memb + (size_t)m * D) + lane + 64 * j) = w; }
;             } }
.LBB0_453:
	v_lshl_add_u64 v[6:7], v[170:171], 4, s[38:39]
	s_lshl_b64 s[22:23], s[40:41], 11
	global_load_dwordx4 v[2:5], v[6:7], off
	global_load_dwordx4 v[10:13], v[6:7], off offset:1024
	global_load_dwordx4 v[14:17], v[6:7], off offset:2048
	global_load_dwordx4 v[18:21], v[6:7], off offset:3072
	v_lshl_add_u64 v[8:9], v[0:1], 0, s[22:23]
	s_add_u32 s12, s12, s84
	s_addc_u32 s13, s13, s85
	s_add_u32 s8, s8, s58
	s_addc_u32 s9, s9, s59
	s_waitcnt vmcnt(3)
	v_cvt_pk_bf16_f32 v2, v2, v3
	v_cvt_pk_bf16_f32 v3, v4, v5
	global_store_dwordx2 v[8:9], v[2:3], off
	s_waitcnt vmcnt(3)
	v_cvt_pk_bf16_f32 v10, v10, v11
	v_cvt_pk_bf16_f32 v11, v12, v13
	global_store_dwordx2 v[8:9], v[10:11], off offset:512
	s_waitcnt vmcnt(3)
	v_cvt_pk_bf16_f32 v14, v14, v15
	v_cvt_pk_bf16_f32 v15, v16, v17
	global_store_dwordx2 v[8:9], v[14:15], off offset:1024
	s_waitcnt vmcnt(3)
	v_cvt_pk_bf16_f32 v18, v18, v19
	v_cvt_pk_bf16_f32 v19, v20, v21
	global_store_dwordx2 v[8:9], v[18:19], off offset:1536
	s_cmpk_gt_i32 s12, 0x13ff
	s_cbranch_scc1 .LBB0_456
